# one in-loop copy slot per gate/up K-iteration (a quarter of the plain-copy units), counted vmcnt adjusted
# baseline (speedup 1.0000x reference)
.LBB0_1208:
	s_add_i32 s95, s95, 1
	s_mul_i32 s8, s95, s40
	s_mov_b32 s82, s40
	s_cmpk_gt_i32 s8, 0x3bff
	s_cbranch_scc1 .LBB0_1379
.LBB0_1209:
	v_readlane_b32 s10, v240, 0
	s_add_i32 s12, s8, s10
	s_lshl_b32 s8, s95, 8
	s_add_i32 s8, s8, s15
	s_ashr_i32 s9, s8, 7
	v_readlane_b32 s11, v240, 1
	s_mul_hi_i32 s10, s9, 0x55555556
	s_lshr_b32 s11, s10, 31
	s_add_i32 s10, s10, s11
	s_mul_i32 s11, s14, 3
	s_add_i32 s11, s10, s11
	s_mul_i32 s10, s10, 3
	s_mul_i32 s11, s11, 3
	s_sub_i32 s10, s9, s10
	s_add_i32 s11, s11, s10
	s_mul_hi_i32 s10, s8, 0x30c30c31
	s_lshr_b32 s16, s10, 31
	s_ashr_i32 s10, s10, 4
	s_add_i32 s10, s10, s16
	s_lshl_b32 s16, s10, 3
	s_or_b32 s16, s16, s14
	s_mulk_i32 s10, 0x54
	s_mulk_i32 s16, 0x54
	s_sub_i32 s10, s8, s10
	s_add_i32 s13, s12, 0x2a00
	s_add_i32 s96, s12, 0xffffdc00
	s_add_i32 s16, s16, s10
	s_cmp_lt_u32 s9, 12
	s_cselect_b32 s10, s19, s2
	s_add_i32 s10, s10, s9
	s_cmp_lt_i32 s9, 9
	s_cselect_b32 s9, s11, s10
	s_lshl_b32 s9, s9, 7
	s_add_i32 s17, s9, s35
	s_cmpk_lt_i32 s8, 0x540
	s_cselect_b32 s10, s16, -1
	s_and_b64 s[8:9], s[58:59], exec
	s_cselect_b32 s16, s12, s10
	s_cmpk_gt_i32 s12, 0x29ff
	s_cselect_b64 s[8:9], -1, 0
	s_and_b64 s[10:11], s[8:9], exec
	s_cselect_b32 s97, -1, s16
	s_or_b64 s[8:9], s[8:9], s[58:59]
	s_cmpk_lt_u32 s96, 0x1800
	s_cselect_b64 s[10:11], -1, 0
	s_and_b64 s[74:75], s[8:9], s[10:11]
	s_and_b64 s[8:9], s[58:59], exec
	s_cselect_b32 s8, s13, s17
	s_cmpk_lt_i32 s12, 0x3800
	s_mov_b32 s40, s82
	s_cselect_b32 s52, s8, -1
	s_mov_b64 s[76:77], -1
	s_mov_b32 s10, s57
	s_branch .LBB0_1212

.LBB0_1649:
	s_or_b64 exec, exec, s[6:7]
	s_add_u32 s8, s30, 0xfc00000
	s_addc_u32 s9, s31, 0
	v_mov_b32_e32 v10, v164
	s_waitcnt lgkmcnt(0)
	s_barrier
	s_cmpk_gt_i32 s69, 0x5d7
	v_readfirstlane_b32 s7, v10
	s_cbranch_scc1 .LBB0_1665
	v_writelane_b32 v247, s78, 0
	v_writelane_b32 v247, s79, 1
	v_writelane_b32 v247, s4, 2
	v_writelane_b32 v247, s5, 3
	s_lshr_b32 s32, s69, 7
	s_lshl_b32 s32, s32, 3
	s_load_dwordx2 s[96:97], s[0:1], s32 offset:0x20
	s_load_dwordx2 s[76:77], s[0:1], 0xa0
	s_and_b32 s100, s69, 0x7f
	s_mul_i32 s100, s100, 0x300000
	s_mov_b32 s101, 0x1ee80000
	s_cmp_lt_u32 s69, 0x80
	s_cselect_b32 s101, 0x6e80000, s101
	v_and_b32_e32 v246, 63, v164
	v_lshlrev_b32_e32 v246, 4, v246
	s_waitcnt lgkmcnt(0)
	s_add_u32 s96, s96, s100
	s_addc_u32 s97, s97, 0
	s_add_u32 s96, s96, 0x3000
	s_addc_u32 s97, s97, 0
	s_and_b32 s97, s97, 0xffff
	s_mov_b32 s98, 0x300000
	s_mov_b32 s99, 0x20000
	s_add_u32 s76, s76, s101
	s_addc_u32 s77, s77, 0
	s_add_u32 s76, s76, s100
	s_addc_u32 s77, s77, 0
	s_and_b32 s77, s77, 0xffff
	s_mov_b32 s78, 0x300000
	s_mov_b32 s79, 0x20000
	s_lshr_b32 s32, s7, 6
	s_mul_i32 s101, s32, 0x12000
	s_add_u32 s100, s101, 0x400
	s_mul_i32 s5, s32, 0x6000
	s_add_u32 s5, s5, 0x90000
	s_mov_b32 s32, 1
	s_mov_b32 s4, 36
	s_mov_b32 s5, 0x70000000
	v_add_u32_e32 v238, 0x1000, v246
	v_add_u32_e32 v239, 0x2000, v246
	buffer_load_dwordx4 v[228:231], v246, s[96:99], s101 offen offset:0 nt
	v_lshlrev_b32_e32 v0, 4, v10
	v_add_u32_e32 v1, 0x2000, v0
	v_ashrrev_i32_e32 v2, 31, v1
	v_lshrrev_b32_e32 v2, 22, v2
	v_add_u32_e32 v2, v1, v2
	v_ashrrev_i32_e32 v8, 10, v2
	v_mul_i32_i24_e32 v2, 0x400, v8
	v_sub_u32_e32 v1, v1, v2
	v_lshrrev_b32_e32 v2, 4, v1
	v_bitop3_b32 v1, v2, v1, 32 bitop3:0x6c
	v_ashrrev_i32_e32 v2, 31, v1
	v_lshrrev_b32_e32 v2, 26, v2
	v_add_u32_e32 v2, v1, v2
	v_lshlrev_b32_e32 v3, 3, v8
	v_ashrrev_i32_e32 v9, 6, v2
	v_and_b32_e32 v3, -16, v3
	v_add_u32_e32 v3, v9, v3
	v_and_b32_e32 v4, 3, v9
	s_mov_b32 s6, 0x1fffe0
	v_lshrrev_b32_e32 v5, 2, v3
	v_lshlrev_b32_e32 v6, 1, v3
	v_and_b32_e32 v2, 0xc0, v2
	v_and_or_b32 v4, v3, s6, v4
	v_and_b32_e32 v5, 4, v5
	v_and_b32_e32 v6, 24, v6
	v_sub_u32_e32 v1, v1, v2
	v_mov_b32_e32 v2, 1
	v_or3_b32 v4, v4, v5, v6
	v_lshlrev_b32_e32 v5, 5, v8
	v_ashrrev_i16_sdwa v1, v2, sext(v1) dst_sel:DWORD dst_unused:UNUSED_PAD src0_sel:DWORD src1_sel:BYTE_0
	v_and_b32_e32 v5, 32, v5
	v_bfe_i32 v11, v1, 0, 16
	v_add_lshl_u32 v1, v5, v11, 1
	v_lshl_add_u32 v130, v4, 11, v1
	v_lshl_add_u32 v132, v3, 11, v1
	v_bfe_i32 v1, v10, 27, 1
	v_lshrrev_b32_e32 v1, 22, v1
	v_add_u32_e32 v1, v0, v1
	v_and_b32_e32 v1, 0xfffffc00, v1
	v_sub_u32_e32 v0, v0, v1
	v_lshrrev_b32_e32 v1, 4, v0
	v_ashrrev_i32_e32 v3, 31, v10
	v_bitop3_b32 v0, v1, v0, 32 bitop3:0x6c
	v_lshrrev_b32_e32 v3, 26, v3
	v_ashrrev_i32_e32 v1, 31, v0
	v_add_u32_e32 v3, v10, v3
	v_lshrrev_b32_e32 v1, 26, v1
	v_ashrrev_i32_e32 v13, 6, v3
	v_add_u32_e32 v1, v0, v1
	v_lshlrev_b32_e32 v3, 3, v13
	v_ashrrev_i32_e32 v12, 6, v1
	v_and_b32_e32 v3, -16, v3
	v_add_u32_e32 v3, v12, v3
	v_and_b32_e32 v4, 3, v12
	s_ashr_i32 s14, s69, 31
	v_and_or_b32 v4, v3, s6, v4
	s_lshr_b32 s6, s14, 29
	s_add_i32 s6, s69, s6
	s_ashr_i32 s2, s7, 6
	s_ashr_i32 s11, s6, 3
	s_and_b32 s6, s6, -8
	s_ashr_i32 s10, s7, 8
	s_lshl_b32 s3, s2, 10
	s_sub_i32 s6, s69, s6
	s_cmp_lt_i32 s6, 0
	s_movk_i32 s15, 0xbc
	s_cselect_b32 s18, s15, 0xbb
	s_mul_i32 s6, s6, s18
	s_add_i32 s6, s6, s11
	s_mul_hi_i32 s11, s6, 0x2e8ba2e9
	s_lshr_b32 s18, s11, 31
	s_ashr_i32 s11, s11, 5
	v_lshrrev_b32_e32 v5, 2, v3
	v_lshlrev_b32_e32 v6, 1, v3
	v_and_b32_e32 v1, 0xc0, v1
	s_add_i32 s11, s11, s18
	v_and_b32_e32 v5, 4, v5
	v_and_b32_e32 v6, 24, v6
	v_sub_u32_e32 v0, v0, v1
	s_lshl_b32 s22, s11, 3
	v_or3_b32 v4, v4, v5, v6
	v_lshlrev_b32_e32 v5, 5, v13
	v_ashrrev_i16_sdwa v0, v2, sext(v0) dst_sel:DWORD dst_unused:UNUSED_PAD src0_sel:DWORD src1_sel:BYTE_0
	s_sub_i32 s18, 0x44, s22
	s_mulk_i32 s11, 0xb0
	v_and_b32_e32 v5, 32, v5
	v_bfe_i32 v14, v0, 0, 16
	s_min_u32 s23, s18, 8
	s_sub_i32 s11, s6, s11
	v_add_lshl_u32 v0, v5, v14, 1
	s_sext_i32_i16 s6, s11
	v_cvt_f32_ubyte0_e32 v2, s23
	v_lshl_add_u32 v134, v4, 11, v0
	v_cvt_f32_i32_e32 v1, s6
	v_rcp_iflag_f32_e32 v4, v2
	v_lshl_add_u32 v136, v3, 11, v0
	s_ashr_i32 s6, s6, 30
	s_or_b32 s6, s6, 1
	v_mul_f32_e32 v0, v1, v4
	v_trunc_f32_e32 v0, v0
	v_fma_f32 v1, -v0, v2, v1
	v_cvt_i32_f32_e32 v0, v0
	v_cmp_ge_f32_e64 s[18:19], |v1|, v2
	s_and_b64 s[18:19], s[18:19], exec
	s_cselect_b32 s6, s6, 0
	v_readfirstlane_b32 s18, v0
	s_add_i32 s6, s18, s6
	s_mul_i32 s18, s6, s23
	s_sub_i32 s11, s11, s18
	s_sext_i32_i16 s11, s11
	s_add_i32 s56, s22, s11
	s_ashr_i32 s57, s56, 31
	s_bfe_i64 s[18:19], s[6:7], 0x100000
	s_lshl_b64 s[22:23], s[56:57], 19
	s_lshl_b64 s[18:19], s[18:19], 19
	s_add_u32 s60, s92, s18
	s_addc_u32 s61, s93, s19
	s_add_i32 s18, s3, 0
	s_add_i32 m0, s18, 0x10000
	v_mov_b32_e32 v139, 0
	global_load_lds_dwordx4 v134, s[60:61]
	s_add_i32 m0, s18, 0x12000
	s_add_u32 s24, s60, 0x40000
	global_load_lds_dwordx4 v130, s[60:61]
	s_addc_u32 s25, s61, 0
	s_add_i32 m0, s18, 0x14000
	v_mov_b32_e32 v135, v139
	global_load_lds_dwordx4 v134, s[24:25]
	s_add_i32 m0, s18, 0x16000
	s_add_u32 s58, s94, s22
	s_addc_u32 s59, s95, s23
	s_add_i32 s19, s18, 0x2000
	global_load_lds_dwordx4 v130, s[24:25]
	s_mov_b32 m0, s18
	s_add_u32 s22, s58, 0x40000
	global_load_lds_dwordx4 v136, s[58:59]
	s_mov_b32 m0, s19
	s_addc_u32 s23, s59, 0
	s_add_i32 s35, s18, 0x4000
	global_load_lds_dwordx4 v132, s[58:59]
	s_mov_b32 m0, s35
	s_add_i32 s43, s18, 0x6000
	global_load_lds_dwordx4 v136, s[22:23]
	s_mov_b32 m0, s43
	v_mov_b32_e32 v131, v139
	global_load_lds_dwordx4 v132, s[22:23]
	v_mov_b32_e32 v137, v139
	v_mov_b32_e32 v133, v139
	s_cmp_eq_u32 s10, 1
	s_mov_b32 s11, 0
	v_lshl_add_u64 v[6:7], s[60:61], 0, v[134:135]
	v_lshl_add_u64 v[4:5], s[60:61], 0, v[130:131]
	v_lshl_add_u64 v[0:1], s[58:59], 0, v[136:137]
	s_cselect_b64 s[22:23], -1, 0
	s_cmp_lg_u32 s10, 1
	v_lshl_add_u64 v[2:3], s[58:59], 0, v[132:133]
	s_cbranch_scc1 .LBB0_1652
	s_barrier

.LBB0_1658:
	ds_read_b128 v[152:155], v149
	ds_read_b128 v[156:159], v149 offset:1024
	ds_read_b128 v[160:163], v149 offset:2048
	ds_read_b128 v[166:169], v149 offset:3072
	ds_read_b128 v[170:173], v150
	ds_read_b128 v[174:177], v150 offset:1024
	ds_read_b128 v[178:181], v150 offset:2048
	ds_read_b128 v[182:185], v150 offset:3072
	s_add_u32 s50, s58, 0xfffc0080
	s_addc_u32 s51, s59, -1
	s_cmp_eq_u32 s49, 12
	s_cselect_b32 s63, s33, s51
	s_cselect_b32 s62, s34, s50
	s_cselect_b32 s61, s37, s48
	s_cselect_b32 s60, s39, s42
	v_lshl_add_u64 v[218:219], s[58:59], 0, v[140:141]
	s_add_i32 m0, s18, 0xc000
	ds_read_b128 v[186:189], v151
	ds_read_b128 v[190:193], v151 offset:1024
	ds_read_b128 v[194:197], v151 offset:2048
	ds_read_b128 v[198:201], v151 offset:3072
	ds_read_b128 v[202:205], v151 offset:4096
	ds_read_b128 v[206:209], v151 offset:5120
	ds_read_b128 v[210:213], v151 offset:6144
	ds_read_b128 v[214:217], v151 offset:7168
	global_load_lds_dwordx4 v[218:219], off
	v_lshl_add_u64 v[218:219], s[58:59], 0, v[142:143]
	s_add_i32 m0, s18, 0xe000
	s_nop 0
	global_load_lds_dwordx4 v[218:219], off
	s_waitcnt vmcnt(9)
	s_waitcnt lgkmcnt(0)
	s_barrier
	s_setprio 1
	s_waitcnt lgkmcnt(0)
	v_mfma_f32_16x16x32_bf16 v[124:127], v[152:155], v[186:189], v[124:127]
	v_mfma_f32_16x16x32_bf16 v[120:123], v[160:163], v[186:189], v[120:123]
	v_mfma_f32_16x16x32_bf16 v[108:111], v[152:155], v[194:197], v[108:111]
	v_mfma_f32_16x16x32_bf16 v[104:107], v[160:163], v[194:197], v[104:107]
	v_mfma_f32_16x16x32_bf16 v[92:95], v[152:155], v[202:205], v[92:95]
	v_mfma_f32_16x16x32_bf16 v[88:91], v[160:163], v[202:205], v[88:91]
	v_mfma_f32_16x16x32_bf16 v[76:79], v[152:155], v[210:213], v[76:79]
	v_mfma_f32_16x16x32_bf16 v[72:75], v[160:163], v[210:213], v[72:75]
	v_mfma_f32_16x16x32_bf16 v[124:127], v[156:159], v[190:193], v[124:127]
	v_mfma_f32_16x16x32_bf16 v[120:123], v[166:169], v[190:193], v[120:123]
	v_mfma_f32_16x16x32_bf16 v[108:111], v[156:159], v[198:201], v[108:111]
	v_mfma_f32_16x16x32_bf16 v[104:107], v[166:169], v[198:201], v[104:107]
	v_mfma_f32_16x16x32_bf16 v[92:95], v[156:159], v[206:209], v[92:95]
	v_mfma_f32_16x16x32_bf16 v[88:91], v[166:169], v[206:209], v[88:91]
	v_mfma_f32_16x16x32_bf16 v[76:79], v[156:159], v[214:217], v[76:79]
	v_mfma_f32_16x16x32_bf16 v[72:75], v[166:169], v[214:217], v[72:75]
	s_setprio 0
	s_setprio 1
	v_mfma_f32_16x16x32_bf16 v[116:119], v[170:173], v[186:189], v[116:119]
	v_mfma_f32_16x16x32_bf16 v[112:115], v[178:181], v[186:189], v[112:115]
	v_mfma_f32_16x16x32_bf16 v[100:103], v[170:173], v[194:197], v[100:103]
	v_mfma_f32_16x16x32_bf16 v[96:99], v[178:181], v[194:197], v[96:99]
	v_mfma_f32_16x16x32_bf16 v[84:87], v[170:173], v[202:205], v[84:87]
	v_mfma_f32_16x16x32_bf16 v[80:83], v[178:181], v[202:205], v[80:83]
	v_mfma_f32_16x16x32_bf16 v[68:71], v[170:173], v[210:213], v[68:71]
	v_mfma_f32_16x16x32_bf16 v[64:67], v[178:181], v[210:213], v[64:67]
	v_mfma_f32_16x16x32_bf16 v[116:119], v[174:177], v[190:193], v[116:119]
	v_mfma_f32_16x16x32_bf16 v[112:115], v[182:185], v[190:193], v[112:115]
	v_mfma_f32_16x16x32_bf16 v[100:103], v[174:177], v[198:201], v[100:103]
	v_mfma_f32_16x16x32_bf16 v[96:99], v[182:185], v[198:201], v[96:99]
	v_mfma_f32_16x16x32_bf16 v[84:87], v[174:177], v[206:209], v[84:87]
	v_mfma_f32_16x16x32_bf16 v[80:83], v[182:185], v[206:209], v[80:83]
	v_mfma_f32_16x16x32_bf16 v[68:71], v[174:177], v[214:217], v[68:71]
	v_mfma_f32_16x16x32_bf16 v[64:67], v[182:185], v[214:217], v[64:67]
	s_setprio 0
	s_barrier
	s_add_i32 s50, s64, s3
	v_lshl_add_u64 v[218:219], s[60:61], 0, v[134:135]
	s_mov_b32 m0, s50
	ds_read_b128 v[186:189], v151 offset:16384
	ds_read_b128 v[190:193], v151 offset:17408
	ds_read_b128 v[194:197], v151 offset:18432
	ds_read_b128 v[198:201], v151 offset:19456
	ds_read_b128 v[202:205], v151 offset:20480
	ds_read_b128 v[206:209], v151 offset:21504
	ds_read_b128 v[210:213], v151 offset:22528
	ds_read_b128 v[214:217], v151 offset:23552
	global_load_lds_dwordx4 v[218:219], off
	s_add_i32 m0, s50, 0x2000
	s_add_u32 s50, s60, 0x40000
	v_lshl_add_u64 v[220:221], s[60:61], 0, v[130:131]
	s_addc_u32 s51, s61, 0
	s_add_i32 s57, s65, s3
	global_load_lds_dwordx4 v[220:221], off
	v_lshl_add_u64 v[222:223], s[50:51], 0, v[134:135]
	s_mov_b32 m0, s57
	v_lshl_add_u64 v[224:225], s[62:63], 0, v[132:133]
	global_load_lds_dwordx4 v[222:223], off
	v_lshl_add_u64 v[222:223], s[50:51], 0, v[130:131]
	s_add_i32 m0, s57, 0x2000
	s_nop 0
	global_load_lds_dwordx4 v[222:223], off
	v_lshl_add_u64 v[222:223], s[62:63], 0, v[136:137]
	s_mov_b32 m0, s18
	s_nop 0
	global_load_lds_dwordx4 v[222:223], off
	s_mov_b32 m0, s19
	s_nop 0
	global_load_lds_dwordx4 v[224:225], off
	s_waitcnt vmcnt(8)
	s_waitcnt lgkmcnt(0)
	s_barrier
	s_setprio 1
	s_waitcnt lgkmcnt(0)
	v_mfma_f32_16x16x32_bf16 v[60:63], v[152:155], v[186:189], v[60:63]
	v_mfma_f32_16x16x32_bf16 v[56:59], v[160:163], v[186:189], v[56:59]
	v_mfma_f32_16x16x32_bf16 v[44:47], v[152:155], v[194:197], v[44:47]
	v_mfma_f32_16x16x32_bf16 v[40:43], v[160:163], v[194:197], v[40:43]
	v_mfma_f32_16x16x32_bf16 v[28:31], v[152:155], v[202:205], v[28:31]
	v_mfma_f32_16x16x32_bf16 v[24:27], v[160:163], v[202:205], v[24:27]
	v_mfma_f32_16x16x32_bf16 v[12:15], v[152:155], v[210:213], v[12:15]
	v_mfma_f32_16x16x32_bf16 v[8:11], v[160:163], v[210:213], v[8:11]
	v_mfma_f32_16x16x32_bf16 v[60:63], v[156:159], v[190:193], v[60:63]
	v_mfma_f32_16x16x32_bf16 v[56:59], v[166:169], v[190:193], v[56:59]
	v_mfma_f32_16x16x32_bf16 v[44:47], v[156:159], v[198:201], v[44:47]
	v_mfma_f32_16x16x32_bf16 v[40:43], v[166:169], v[198:201], v[40:43]
	v_mfma_f32_16x16x32_bf16 v[28:31], v[156:159], v[206:209], v[28:31]
	v_mfma_f32_16x16x32_bf16 v[24:27], v[166:169], v[206:209], v[24:27]
	v_mfma_f32_16x16x32_bf16 v[12:15], v[156:159], v[214:217], v[12:15]
	v_mfma_f32_16x16x32_bf16 v[8:11], v[166:169], v[214:217], v[8:11]
	s_setprio 0
	s_setprio 1
	v_mfma_f32_16x16x32_bf16 v[52:55], v[170:173], v[186:189], v[52:55]
	v_mfma_f32_16x16x32_bf16 v[48:51], v[178:181], v[186:189], v[48:51]
	v_mfma_f32_16x16x32_bf16 v[36:39], v[170:173], v[194:197], v[36:39]
	v_mfma_f32_16x16x32_bf16 v[32:35], v[178:181], v[194:197], v[32:35]
	v_mfma_f32_16x16x32_bf16 v[20:23], v[170:173], v[202:205], v[20:23]
	v_mfma_f32_16x16x32_bf16 v[16:19], v[178:181], v[202:205], v[16:19]
	v_mfma_f32_16x16x32_bf16 v[4:7], v[170:173], v[210:213], v[4:7]
	v_mfma_f32_16x16x32_bf16 v[0:3], v[178:181], v[210:213], v[0:3]
	v_mfma_f32_16x16x32_bf16 v[52:55], v[174:177], v[190:193], v[52:55]
	v_mfma_f32_16x16x32_bf16 v[48:51], v[182:185], v[190:193], v[48:51]
	v_mfma_f32_16x16x32_bf16 v[36:39], v[174:177], v[198:201], v[36:39]
	v_mfma_f32_16x16x32_bf16 v[32:35], v[182:185], v[198:201], v[32:35]
	v_mfma_f32_16x16x32_bf16 v[20:23], v[174:177], v[206:209], v[20:23]
	v_mfma_f32_16x16x32_bf16 v[16:19], v[182:185], v[206:209], v[16:19]
	v_mfma_f32_16x16x32_bf16 v[4:7], v[174:177], v[214:217], v[4:7]
	v_mfma_f32_16x16x32_bf16 v[0:3], v[182:185], v[214:217], v[0:3]
	s_setprio 0
	s_barrier
	buffer_store_dwordx4 v[228:231], v246, s[76:79], s101 offen offset:0 nt
	s_add_i32 s57, 0, 0x18000
	v_add_u32_e32 v165, s57, v148
	s_add_i32 s68, 0, 0x1c000
	ds_read_b128 v[152:155], v165
	ds_read_b128 v[156:159], v165 offset:1024
	ds_read_b128 v[160:163], v165 offset:2048
	ds_read_b128 v[166:169], v165 offset:3072
	v_add_u32_e32 v165, s68, v148
	ds_read_b128 v[170:173], v165
	ds_read_b128 v[174:177], v165 offset:1024
	ds_read_b128 v[178:181], v165 offset:2048
	ds_read_b128 v[182:185], v165 offset:3072
	s_add_u32 s50, s62, 0x40000
	s_addc_u32 s51, s63, 0
	s_mov_b32 m0, s35
	v_lshl_add_u64 v[226:227], s[50:51], 0, v[136:137]
	ds_read_b128 v[186:189], v151 offset:32768
	ds_read_b128 v[190:193], v151 offset:33792
	ds_read_b128 v[194:197], v151 offset:34816
	ds_read_b128 v[198:201], v151 offset:35840
	ds_read_b128 v[202:205], v151 offset:36864
	ds_read_b128 v[206:209], v151 offset:37888
	ds_read_b128 v[210:213], v151 offset:38912
	ds_read_b128 v[214:217], v151 offset:39936
	global_load_lds_dwordx4 v[226:227], off
	v_lshl_add_u64 v[226:227], s[50:51], 0, v[132:133]
	s_mov_b32 m0, s43
	s_nop 0
	global_load_lds_dwordx4 v[226:227], off
	buffer_load_dwordx4 v[228:231], v246, s[96:99], s100 offen offset:0 nt
	s_waitcnt vmcnt(10)
	s_waitcnt lgkmcnt(0)
	s_barrier
	s_setprio 1
	s_waitcnt lgkmcnt(0)
	v_mfma_f32_16x16x32_bf16 v[124:127], v[152:155], v[186:189], v[124:127]
	v_mfma_f32_16x16x32_bf16 v[120:123], v[160:163], v[186:189], v[120:123]
	v_mfma_f32_16x16x32_bf16 v[108:111], v[152:155], v[194:197], v[108:111]
	v_mfma_f32_16x16x32_bf16 v[104:107], v[160:163], v[194:197], v[104:107]
	v_mfma_f32_16x16x32_bf16 v[92:95], v[152:155], v[202:205], v[92:95]
	v_mfma_f32_16x16x32_bf16 v[88:91], v[160:163], v[202:205], v[88:91]
	v_mfma_f32_16x16x32_bf16 v[76:79], v[152:155], v[210:213], v[76:79]
	v_mfma_f32_16x16x32_bf16 v[72:75], v[160:163], v[210:213], v[72:75]
	v_mfma_f32_16x16x32_bf16 v[124:127], v[156:159], v[190:193], v[124:127]
	v_mfma_f32_16x16x32_bf16 v[120:123], v[166:169], v[190:193], v[120:123]
	v_mfma_f32_16x16x32_bf16 v[108:111], v[156:159], v[198:201], v[108:111]
	v_mfma_f32_16x16x32_bf16 v[104:107], v[166:169], v[198:201], v[104:107]
	v_mfma_f32_16x16x32_bf16 v[92:95], v[156:159], v[206:209], v[92:95]
	v_mfma_f32_16x16x32_bf16 v[88:91], v[166:169], v[206:209], v[88:91]
	v_mfma_f32_16x16x32_bf16 v[76:79], v[156:159], v[214:217], v[76:79]
	v_mfma_f32_16x16x32_bf16 v[72:75], v[166:169], v[214:217], v[72:75]
	s_setprio 0
	s_setprio 1
	v_mfma_f32_16x16x32_bf16 v[116:119], v[170:173], v[186:189], v[116:119]
	v_mfma_f32_16x16x32_bf16 v[112:115], v[178:181], v[186:189], v[112:115]
	v_mfma_f32_16x16x32_bf16 v[100:103], v[170:173], v[194:197], v[100:103]
	v_mfma_f32_16x16x32_bf16 v[96:99], v[178:181], v[194:197], v[96:99]
	v_mfma_f32_16x16x32_bf16 v[84:87], v[170:173], v[202:205], v[84:87]
	v_mfma_f32_16x16x32_bf16 v[80:83], v[178:181], v[202:205], v[80:83]
	v_mfma_f32_16x16x32_bf16 v[68:71], v[170:173], v[210:213], v[68:71]
	v_mfma_f32_16x16x32_bf16 v[64:67], v[178:181], v[210:213], v[64:67]
	v_mfma_f32_16x16x32_bf16 v[116:119], v[174:177], v[190:193], v[116:119]
	v_mfma_f32_16x16x32_bf16 v[112:115], v[182:185], v[190:193], v[112:115]
	v_mfma_f32_16x16x32_bf16 v[100:103], v[174:177], v[198:201], v[100:103]
	v_mfma_f32_16x16x32_bf16 v[96:99], v[182:185], v[198:201], v[96:99]
	v_mfma_f32_16x16x32_bf16 v[84:87], v[174:177], v[206:209], v[84:87]
	v_mfma_f32_16x16x32_bf16 v[80:83], v[182:185], v[206:209], v[80:83]
	v_mfma_f32_16x16x32_bf16 v[68:71], v[174:177], v[214:217], v[68:71]
	v_mfma_f32_16x16x32_bf16 v[64:67], v[182:185], v[214:217], v[64:67]
	s_setprio 0
	s_barrier
	s_add_i32 s50, s57, s3
	v_lshl_add_u64 v[218:219], v[218:219], 0, s[24:25]
	s_mov_b32 m0, s50
	ds_read_b128 v[186:189], v151 offset:49152
	ds_read_b128 v[190:193], v151 offset:50176
	ds_read_b128 v[194:197], v151 offset:51200
	ds_read_b128 v[198:201], v151 offset:52224
	ds_read_b128 v[202:205], v151 offset:53248
	ds_read_b128 v[206:209], v151 offset:54272
	ds_read_b128 v[210:213], v151 offset:55296
	ds_read_b128 v[214:217], v151 offset:56320
	global_load_lds_dwordx4 v[218:219], off
	s_add_i32 m0, s50, 0x2000
	s_add_u32 s50, s60, 0x40080
	v_lshl_add_u64 v[218:219], v[220:221], 0, s[24:25]
	s_addc_u32 s51, s61, 0
	s_add_i32 s57, s68, s3
	global_load_lds_dwordx4 v[218:219], off
	v_lshl_add_u64 v[218:219], s[50:51], 0, v[134:135]
	s_mov_b32 m0, s57
	s_nop 0
	global_load_lds_dwordx4 v[218:219], off
	v_lshl_add_u64 v[218:219], s[50:51], 0, v[130:131]
	s_add_i32 m0, s57, 0x2000
	s_nop 0
	global_load_lds_dwordx4 v[218:219], off
	v_lshl_add_u64 v[218:219], v[222:223], 0, s[24:25]
	s_mov_b32 m0, s44
	s_nop 0
	global_load_lds_dwordx4 v[218:219], off
	v_lshl_add_u64 v[218:219], v[224:225], 0, s[24:25]
	s_mov_b32 m0, s45
	s_nop 0
	global_load_lds_dwordx4 v[218:219], off
	s_waitcnt vmcnt(10)
	s_waitcnt lgkmcnt(0)
	s_barrier
	s_setprio 1
	s_waitcnt lgkmcnt(0)
	v_mfma_f32_16x16x32_bf16 v[60:63], v[152:155], v[186:189], v[60:63]
	v_mfma_f32_16x16x32_bf16 v[56:59], v[160:163], v[186:189], v[56:59]
	v_mfma_f32_16x16x32_bf16 v[44:47], v[152:155], v[194:197], v[44:47]
	v_mfma_f32_16x16x32_bf16 v[40:43], v[160:163], v[194:197], v[40:43]
	v_mfma_f32_16x16x32_bf16 v[28:31], v[152:155], v[202:205], v[28:31]
	v_mfma_f32_16x16x32_bf16 v[24:27], v[160:163], v[202:205], v[24:27]
	v_mfma_f32_16x16x32_bf16 v[12:15], v[152:155], v[210:213], v[12:15]
	v_mfma_f32_16x16x32_bf16 v[8:11], v[160:163], v[210:213], v[8:11]
	v_mfma_f32_16x16x32_bf16 v[60:63], v[156:159], v[190:193], v[60:63]
	v_mfma_f32_16x16x32_bf16 v[56:59], v[166:169], v[190:193], v[56:59]
	v_mfma_f32_16x16x32_bf16 v[44:47], v[156:159], v[198:201], v[44:47]
	v_mfma_f32_16x16x32_bf16 v[40:43], v[166:169], v[198:201], v[40:43]
	v_mfma_f32_16x16x32_bf16 v[28:31], v[156:159], v[206:209], v[28:31]
	v_mfma_f32_16x16x32_bf16 v[24:27], v[166:169], v[206:209], v[24:27]
	v_mfma_f32_16x16x32_bf16 v[12:15], v[156:159], v[214:217], v[12:15]
	v_mfma_f32_16x16x32_bf16 v[8:11], v[166:169], v[214:217], v[8:11]
	s_setprio 0
	s_setprio 1
	v_mfma_f32_16x16x32_bf16 v[52:55], v[170:173], v[186:189], v[52:55]
	v_mfma_f32_16x16x32_bf16 v[48:51], v[178:181], v[186:189], v[48:51]
	v_mfma_f32_16x16x32_bf16 v[36:39], v[170:173], v[194:197], v[36:39]
	v_mfma_f32_16x16x32_bf16 v[32:35], v[178:181], v[194:197], v[32:35]
	v_mfma_f32_16x16x32_bf16 v[20:23], v[170:173], v[202:205], v[20:23]
	v_mfma_f32_16x16x32_bf16 v[16:19], v[178:181], v[202:205], v[16:19]
	v_mfma_f32_16x16x32_bf16 v[4:7], v[170:173], v[210:213], v[4:7]
	v_mfma_f32_16x16x32_bf16 v[0:3], v[178:181], v[210:213], v[0:3]
	v_mfma_f32_16x16x32_bf16 v[52:55], v[174:177], v[190:193], v[52:55]
	v_mfma_f32_16x16x32_bf16 v[48:51], v[182:185], v[190:193], v[48:51]
	v_mfma_f32_16x16x32_bf16 v[36:39], v[174:177], v[198:201], v[36:39]
	v_mfma_f32_16x16x32_bf16 v[32:35], v[182:185], v[198:201], v[32:35]
	v_mfma_f32_16x16x32_bf16 v[20:23], v[174:177], v[206:209], v[20:23]
	v_mfma_f32_16x16x32_bf16 v[16:19], v[182:185], v[206:209], v[16:19]
	v_mfma_f32_16x16x32_bf16 v[4:7], v[174:177], v[214:217], v[4:7]
	v_mfma_f32_16x16x32_bf16 v[0:3], v[182:185], v[214:217], v[0:3]
	s_setprio 0
	s_barrier
	s_sub_u32 s4, s4, 1
	s_cmp_eq_u32 s4, 0
	s_cselect_b32 s100, 0x70000000, s100
	s_mov_b32 s101, s100
	s_add_i32 s32, s32, 1
	s_cmp_eq_u32 s32, 12
	s_cselect_b32 vcc_lo, 0x3000, 0
	s_cselect_b32 s32, 0, s32
	s_add_u32 s100, s100, vcc_lo
	s_addk_i32 s100, 0x400
	s_add_i32 s49, s49, 2
	s_add_u32 s58, s58, 0x100
	s_addc_u32 s59, s59, 0
	s_add_u32 s42, s42, 0x100
	s_addc_u32 s48, s48, 0
	s_cmp_gt_u32 s49, 13
	s_cbranch_scc0 .LBB0_1658
	s_and_b64 vcc, exec, s[26:27]
	s_cbranch_vccz .LBB0_1661
	s_barrier
